# weight conversion schedule: w_in-gap workgroups convert the current layer's ffn-up slice (last layer's gap used, 825 fewer jobs in phase 0)
# baseline (speedup 1.0000x reference)
; #define LAS __attribute__((address_space(3)))
; __device__ __forceinline__ int opaque_tid() { int t = threadIdx.x; asm volatile("" : "+v"(t)); return t; }
; template <bool PREPMAP> __device__ __forceinline__ int cvt_map(int q) {
;     if (!PREPMAP) return q;
;     constexpr int NL = (NLAYER - 1) * GAP_PRE;
;     if (q >= NL) return q - NL;
;     return (1 + q / GAP_PRE) * CT_LAYER + q % GAP_PRE;
; }
; template <bool PREPMAP>
; __device__ __forceinline__ void convert_jobs(const Params& p, int job0, int job_end, int stride, LAS unsigned char* lds) {
;     if (job0 >= job_end) return;
;     const int tid = opaque_tid();
;     int job = job0;
;     CvtJob cur = cvt_decode(p, cvt_map<PREPMAP>(job));
.LBB0_11:
	s_or_b64 exec, exec, s[4:5]
	s_mov_b32 s24, s80
	s_cmpk_gt_i32 s80, 0x1852
	s_cbranch_scc1 .LBB0_197
	v_mov_b32_e32 v36, v210
	s_cmpk_lt_i32 s80, 0xf3c
	s_cbranch_scc0 .LBB0_14
	s_mul_hi_i32 s4, s80, 0x64d319ff
	s_lshr_b32 s5, s4, 31
	s_ashr_i32 s4, s4, 9
	s_add_i32 s4, s4, s5
	s_mul_i32 s5, s4, 0xc50
	s_mulk_i32 s4, 0x514
	s_sub_i32 s4, s80, s4
	s_add_i32 s4, s4, s5
	s_add_i32 s7, s4, 0xc50
	s_cbranch_execz .LBB0_15
	s_branch .LBB0_16
.LBB0_14:
.LBB0_15:
	s_add_i32 s7, s80, 0xfffff0c4
	s_add_i32 s4, s7, 0x339
	s_cmpk_lt_i32 s7, 0x514
	s_cselect_b32 s7, s7, s4

; template <bool PREPMAP> __device__ __forceinline__ int cvt_map(int q) {
;     if (!PREPMAP) return q;
;     constexpr int NL = (NLAYER - 1) * GAP_PRE;
;     if (q >= NL) return q - NL;
;     return (1 + q / GAP_PRE) * CT_LAYER + q % GAP_PRE;
; }
; template <bool PREPMAP>
; __device__ __forceinline__ void convert_jobs(const Params& p, int job0, int job_end, int stride, LAS unsigned char* lds) {
;     ...
;     for (;;) {
;         const int nj = job + stride; const bool more = nj < job_end;
;         CvtJob nxt = cur; f32x4 v2[8]; float gk2[8];
;         if (more) { nxt = cvt_decode(p, cvt_map<PREPMAP>(nj)); cvt_load(nxt, tid, v2, gk2); }
.LBB0_106:
	s_load_dwordx2 s[4:5], s[0:1], 0xb0
	s_mov_b64 s[48:49], s[34:35]
	s_mov_b32 s66, s25
	s_mov_b32 s56, s36
	s_mov_b32 s67, s33
	s_waitcnt lgkmcnt(0)
	s_add_i32 s65, s24, s4
	s_cmpk_lt_i32 s65, 0x1853
	s_cselect_b64 s[46:47], -1, 0
	s_cmpk_gt_i32 s65, 0x1852
	s_cselect_b64 s[44:45], -1, 0
	s_and_b64 vcc, exec, s[44:45]
	s_cbranch_vccnz .LBB0_194
	s_cmpk_lt_i32 s65, 0xf3c
	s_mov_b64 s[4:5], -1
	s_cbranch_scc0 .LBB0_109
	s_mul_hi_i32 s4, s65, 0x64d319ff
	s_lshr_b32 s5, s4, 31
	s_ashr_i32 s4, s4, 9
	s_add_i32 s4, s4, s5
	s_mul_i32 s5, s4, 0xc50
	s_mulk_i32 s4, 0x514
	s_sub_i32 s4, s65, s4
	s_add_i32 s4, s4, s5
	s_add_i32 s7, s4, 0xc50
	s_mov_b64 s[4:5], 0
.LBB0_109:
	s_andn2_b64 vcc, exec, s[4:5]
	s_cbranch_vccnz .LBB0_111
	s_add_i32 s7, s65, 0xfffff0c4
	s_add_i32 s4, s7, 0x339
	s_cmpk_lt_i32 s7, 0x514
	s_cselect_b32 s7, s7, s4

; #define LAS __attribute__((address_space(3)))
; __device__ __forceinline__ void convert_gap(const Params& p, int layer, int nwg, int base, int per, LAS unsigned char* lds) {
;     if (layer + 1 >= NLAYER) return;
;     const int G = gridDim.x, c = blockIdx.x, rem = nwg % G;
;     const int limit = base == GAP_PRE ? GAP_BASE6 : CT_LAYER;
;     if (rem == 0) { __syncthreads(); convert_jobs<false>(p, (layer + 1) * CT_LAYER + base + c, (layer + 1) * CT_LAYER + limit, G, lds); return; }
;     if (c < rem) return;
;     const int slot = c - rem, nslots = G - rem;
;     int j0 = base + slot * per, j1 = j0 + per;
;     if (slot == nslots - 1 || j1 > limit) j1 = limit;
;     if (j0 > limit) j0 = limit;
;     __syncthreads();
;     convert_jobs<false>(p, (layer + 1) * CT_LAYER + j0, (layer + 1) * CT_LAYER + j1, 1, lds);
.LBB0_1051:
	v_readlane_b32 s47, v254, 24
	s_barrier
	s_cmpk_gt_i32 s31, 0x7f
	s_cbranch_scc1 .LBB0_1409
.LBB0_1052:
	v_readlane_b32 s0, v253, 56
	v_readlane_b32 s1, v253, 57
	s_add_i32 s2, s90, 0
	s_and_b64 vcc, exec, s[0:1]
	s_cbranch_vccz .LBB0_1063
	v_readlane_b32 s0, v253, 58
	v_readlane_b32 s1, v253, 59
	s_andn2_b64 vcc, exec, s[0:1]
	s_cbranch_vccnz .LBB0_1233
	v_readlane_b32 s0, v254, 3
	v_readlane_b32 s1, v254, 4
	s_andn2_b64 vcc, exec, s[0:1]
	s_waitcnt vmcnt(0) lgkmcnt(0)
	s_barrier
	s_cbranch_vccnz .LBB0_1233
	s_mul_i32 s3, s2, 0xc50
	v_readlane_b32 s0, v254, 0
	s_add_i32 s12, s0, s3
	s_mul_hi_i32 s0, s12, 0x532ae21d
	s_lshr_b32 s1, s0, 31
	s_ashr_i32 s0, s0, 10
	s_add_i32 s10, s0, s1
	v_mul_i32_i24_e32 v0, s10, v218
	s_ashr_i32 s11, s10, 31
	v_readfirstlane_b32 s0, v0
	s_sub_i32 s14, s12, s0
	s_mul_i32 s0, s10, 0x6280000
	s_mul_hi_i32 s1, s10, 0x6280000
	s_add_u32 s0, s34, s0
	s_addc_u32 s1, s35, s1
	v_mov_b32_e32 v36, v210
	s_cmpk_gt_i32 s14, 0x29f
	s_cbranch_scc0 .LBB0_1065
	s_cmpk_gt_u32 s14, 0x2cf
	s_mov_b64 s[22:23], -1
	s_cbranch_scc0 .LBB0_1073
	s_cmpk_gt_u32 s14, 0x30f
	s_cbranch_scc0 .LBB0_1070
	s_cmpk_gt_u32 s14, 0x40f
	s_cbranch_scc0 .LBB0_1067
	s_cmpk_gt_u32 s14, 0x98f
	s_mov_b64 s[16:17], -1
	s_cbranch_scc0 .LBB0_1061
	s_add_i32 s6, s14, 0xfffff670
	s_mul_i32 s8, s10, 0x2c00000
	v_readlane_b32 s9, v254, 36
	s_mul_hi_i32 s7, s10, 0x2c00000
	s_add_u32 s20, s9, s8
	v_readlane_b32 s8, v254, 37
	s_addc_u32 s21, s8, s7
	s_add_u32 s8, s0, 0x4c80000
	s_addc_u32 s9, s1, 0
	s_mov_b64 s[16:17], 0
